# gate/up epilogue: denominator and rs^2 merged by one packed fma per pair (3 pk_mul + 1 pk_fma instead of 4 pk_mul + 2 add), regenerated in blocks
# speedup vs baseline: 1.0031x; 1.0006x over previous
.LBB0_576:
	s_waitcnt vmcnt(8)
	s_mul_i32 s3, s38, 22
	s_add_i32 s2, s3, s2
	s_ashr_i32 s3, s2, 31
	s_lshl_b64 s[2:3], s[2:3], 16
	s_add_u32 s38, s50, s2
	s_addc_u32 s39, s51, s3
	v_mul_f32_e32 v180, 0xbfb8aa3b, v168
	v_mul_f32_e32 v182, v168, v168
	v_rcp_f32_e32 v182, v182
	v_pk_mul_f32 v[184:185], v[180:181], v[116:117] op_sel_hi:[0,1]
	v_pk_mul_f32 v[186:187], v[180:181], v[118:119] op_sel_hi:[0,1]
	v_pk_mul_f32 v[188:189], v[180:181], v[124:125] op_sel_hi:[0,1]
	v_pk_mul_f32 v[190:191], v[180:181], v[126:127] op_sel_hi:[0,1]
	v_exp_f32_e32 v184, v184
	v_exp_f32_e32 v185, v185
	v_exp_f32_e32 v186, v186
	v_exp_f32_e32 v187, v187
	v_exp_f32_e32 v188, v188
	v_exp_f32_e32 v189, v189
	v_exp_f32_e32 v190, v190
	v_exp_f32_e32 v191, v191
	v_pk_mul_f32 v[112:113], v[116:117], v[112:113]
	v_pk_mul_f32 v[114:115], v[118:119], v[114:115]
	v_pk_mul_f32 v[120:121], v[124:125], v[120:121]
	v_pk_mul_f32 v[122:123], v[126:127], v[122:123]
	v_pk_fma_f32 v[184:185], v[184:185], v[182:183], v[182:183] op_sel_hi:[1,0,0]
	v_pk_fma_f32 v[186:187], v[186:187], v[182:183], v[182:183] op_sel_hi:[1,0,0]
	v_pk_fma_f32 v[188:189], v[188:189], v[182:183], v[182:183] op_sel_hi:[1,0,0]
	v_pk_fma_f32 v[190:191], v[190:191], v[182:183], v[182:183] op_sel_hi:[1,0,0]
	v_rcp_f32_e32 v184, v184
	v_rcp_f32_e32 v185, v185
	v_rcp_f32_e32 v186, v186
	v_rcp_f32_e32 v187, v187
	v_rcp_f32_e32 v188, v188
	v_rcp_f32_e32 v189, v189
	v_rcp_f32_e32 v190, v190
	v_rcp_f32_e32 v191, v191
	v_lshl_add_u64 v[178:179], s[38:39], 0, v[136:137]
	v_lshl_add_u64 v[178:179], v[178:179], 0, v[208:209]
	v_pk_mul_f32 v[112:113], v[112:113], v[184:185]
	v_pk_mul_f32 v[114:115], v[114:115], v[186:187]
	v_pk_mul_f32 v[120:121], v[120:121], v[188:189]
	v_pk_mul_f32 v[122:123], v[122:123], v[190:191]
	v_cvt_pk_bf16_f32 v112, v112, v113
	v_cvt_pk_bf16_f32 v113, v114, v115
	v_cvt_pk_bf16_f32 v114, v120, v121
	v_cvt_pk_bf16_f32 v115, v122, v123
	global_store_dwordx4 v[178:179], v[112:115], off sc1 nt
	v_mul_f32_e32 v180, 0xbfb8aa3b, v167
	v_mul_f32_e32 v182, v167, v167
	v_rcp_f32_e32 v182, v182
	v_pk_mul_f32 v[184:185], v[180:181], v[100:101] op_sel_hi:[0,1]
	v_pk_mul_f32 v[186:187], v[180:181], v[102:103] op_sel_hi:[0,1]
	v_pk_mul_f32 v[188:189], v[180:181], v[108:109] op_sel_hi:[0,1]
	v_pk_mul_f32 v[190:191], v[180:181], v[110:111] op_sel_hi:[0,1]
	v_exp_f32_e32 v184, v184
	v_exp_f32_e32 v185, v185
	v_exp_f32_e32 v186, v186
	v_exp_f32_e32 v187, v187
	v_exp_f32_e32 v188, v188
	v_exp_f32_e32 v189, v189
	v_exp_f32_e32 v190, v190
	v_exp_f32_e32 v191, v191
	v_pk_mul_f32 v[96:97], v[100:101], v[96:97]
	v_pk_mul_f32 v[98:99], v[102:103], v[98:99]
	v_pk_mul_f32 v[104:105], v[108:109], v[104:105]
	v_pk_mul_f32 v[106:107], v[110:111], v[106:107]
	v_pk_fma_f32 v[184:185], v[184:185], v[182:183], v[182:183] op_sel_hi:[1,0,0]
	v_pk_fma_f32 v[186:187], v[186:187], v[182:183], v[182:183] op_sel_hi:[1,0,0]
	v_pk_fma_f32 v[188:189], v[188:189], v[182:183], v[182:183] op_sel_hi:[1,0,0]
	v_pk_fma_f32 v[190:191], v[190:191], v[182:183], v[182:183] op_sel_hi:[1,0,0]
	v_rcp_f32_e32 v184, v184
	v_rcp_f32_e32 v185, v185
	v_rcp_f32_e32 v186, v186
	v_rcp_f32_e32 v187, v187
	v_rcp_f32_e32 v188, v188
	v_rcp_f32_e32 v189, v189
	v_rcp_f32_e32 v190, v190
	v_rcp_f32_e32 v191, v191
	v_lshl_add_u64 v[178:179], s[38:39], 0, v[138:139]
	v_lshl_add_u64 v[178:179], v[178:179], 0, v[208:209]
	v_pk_mul_f32 v[96:97], v[96:97], v[184:185]
	v_pk_mul_f32 v[98:99], v[98:99], v[186:187]
	v_pk_mul_f32 v[104:105], v[104:105], v[188:189]
	v_pk_mul_f32 v[106:107], v[106:107], v[190:191]
	v_cvt_pk_bf16_f32 v96, v96, v97
	v_cvt_pk_bf16_f32 v97, v98, v99
	v_cvt_pk_bf16_f32 v98, v104, v105
	v_cvt_pk_bf16_f32 v99, v106, v107
	global_store_dwordx4 v[178:179], v[96:99], off sc1 nt
	v_mul_f32_e32 v180, 0xbfb8aa3b, v166
	v_mul_f32_e32 v182, v166, v166
	v_rcp_f32_e32 v182, v182
	v_pk_mul_f32 v[184:185], v[180:181], v[84:85] op_sel_hi:[0,1]
	v_pk_mul_f32 v[186:187], v[180:181], v[86:87] op_sel_hi:[0,1]
	v_pk_mul_f32 v[188:189], v[180:181], v[92:93] op_sel_hi:[0,1]
	v_pk_mul_f32 v[190:191], v[180:181], v[94:95] op_sel_hi:[0,1]
	v_exp_f32_e32 v184, v184
	v_exp_f32_e32 v185, v185
	v_exp_f32_e32 v186, v186
	v_exp_f32_e32 v187, v187
	v_exp_f32_e32 v188, v188
	v_exp_f32_e32 v189, v189
	v_exp_f32_e32 v190, v190
	v_exp_f32_e32 v191, v191
	v_pk_mul_f32 v[80:81], v[84:85], v[80:81]
	v_pk_mul_f32 v[82:83], v[86:87], v[82:83]
	v_pk_mul_f32 v[88:89], v[92:93], v[88:89]
	v_pk_mul_f32 v[90:91], v[94:95], v[90:91]
	v_pk_fma_f32 v[184:185], v[184:185], v[182:183], v[182:183] op_sel_hi:[1,0,0]
	v_pk_fma_f32 v[186:187], v[186:187], v[182:183], v[182:183] op_sel_hi:[1,0,0]
	v_pk_fma_f32 v[188:189], v[188:189], v[182:183], v[182:183] op_sel_hi:[1,0,0]
	v_pk_fma_f32 v[190:191], v[190:191], v[182:183], v[182:183] op_sel_hi:[1,0,0]
	v_rcp_f32_e32 v184, v184
	v_rcp_f32_e32 v185, v185
	v_rcp_f32_e32 v186, v186
	v_rcp_f32_e32 v187, v187
	v_rcp_f32_e32 v188, v188
	v_rcp_f32_e32 v189, v189
	v_rcp_f32_e32 v190, v190
	v_rcp_f32_e32 v191, v191
	v_lshl_add_u64 v[178:179], s[38:39], 0, v[140:141]
	v_lshl_add_u64 v[178:179], v[178:179], 0, v[208:209]
	v_pk_mul_f32 v[80:81], v[80:81], v[184:185]
	v_pk_mul_f32 v[82:83], v[82:83], v[186:187]
	v_pk_mul_f32 v[88:89], v[88:89], v[188:189]
	v_pk_mul_f32 v[90:91], v[90:91], v[190:191]
	v_cvt_pk_bf16_f32 v80, v80, v81
	v_cvt_pk_bf16_f32 v81, v82, v83
	v_cvt_pk_bf16_f32 v82, v88, v89
	v_cvt_pk_bf16_f32 v83, v90, v91
	global_store_dwordx4 v[178:179], v[80:83], off sc1 nt
	v_mul_f32_e32 v180, 0xbfb8aa3b, v165
	v_mul_f32_e32 v182, v165, v165
	v_rcp_f32_e32 v182, v182
	v_pk_mul_f32 v[184:185], v[180:181], v[68:69] op_sel_hi:[0,1]
	v_pk_mul_f32 v[186:187], v[180:181], v[70:71] op_sel_hi:[0,1]
	v_pk_mul_f32 v[188:189], v[180:181], v[76:77] op_sel_hi:[0,1]
	v_pk_mul_f32 v[190:191], v[180:181], v[78:79] op_sel_hi:[0,1]
	v_exp_f32_e32 v184, v184
	v_exp_f32_e32 v185, v185
	v_exp_f32_e32 v186, v186
	v_exp_f32_e32 v187, v187
	v_exp_f32_e32 v188, v188
	v_exp_f32_e32 v189, v189
	v_exp_f32_e32 v190, v190
	v_exp_f32_e32 v191, v191
	v_pk_mul_f32 v[64:65], v[68:69], v[64:65]
	v_pk_mul_f32 v[66:67], v[70:71], v[66:67]
	v_pk_mul_f32 v[72:73], v[76:77], v[72:73]
	v_pk_mul_f32 v[74:75], v[78:79], v[74:75]
	v_pk_fma_f32 v[184:185], v[184:185], v[182:183], v[182:183] op_sel_hi:[1,0,0]
	v_pk_fma_f32 v[186:187], v[186:187], v[182:183], v[182:183] op_sel_hi:[1,0,0]
	v_pk_fma_f32 v[188:189], v[188:189], v[182:183], v[182:183] op_sel_hi:[1,0,0]
	v_pk_fma_f32 v[190:191], v[190:191], v[182:183], v[182:183] op_sel_hi:[1,0,0]
	v_rcp_f32_e32 v184, v184
	v_rcp_f32_e32 v185, v185
	v_rcp_f32_e32 v186, v186
	v_rcp_f32_e32 v187, v187
	v_rcp_f32_e32 v188, v188
	v_rcp_f32_e32 v189, v189
	v_rcp_f32_e32 v190, v190
	v_rcp_f32_e32 v191, v191
	v_lshl_add_u64 v[178:179], s[38:39], 0, v[142:143]
	v_lshl_add_u64 v[178:179], v[178:179], 0, v[208:209]
	v_pk_mul_f32 v[64:65], v[64:65], v[184:185]
	v_pk_mul_f32 v[66:67], v[66:67], v[186:187]
	v_pk_mul_f32 v[72:73], v[72:73], v[188:189]
	v_pk_mul_f32 v[74:75], v[74:75], v[190:191]
	v_cvt_pk_bf16_f32 v64, v64, v65
	v_cvt_pk_bf16_f32 v65, v66, v67
	v_cvt_pk_bf16_f32 v66, v72, v73
	v_cvt_pk_bf16_f32 v67, v74, v75
	global_store_dwordx4 v[178:179], v[64:67], off sc1 nt
	v_mul_f32_e32 v180, 0xbfb8aa3b, v164
	v_mul_f32_e32 v182, v164, v164
	v_rcp_f32_e32 v182, v182
	v_pk_mul_f32 v[184:185], v[180:181], v[52:53] op_sel_hi:[0,1]
	v_pk_mul_f32 v[186:187], v[180:181], v[54:55] op_sel_hi:[0,1]
	v_pk_mul_f32 v[188:189], v[180:181], v[60:61] op_sel_hi:[0,1]
	v_pk_mul_f32 v[190:191], v[180:181], v[62:63] op_sel_hi:[0,1]
	v_exp_f32_e32 v184, v184
	v_exp_f32_e32 v185, v185
	v_exp_f32_e32 v186, v186
	v_exp_f32_e32 v187, v187
	v_exp_f32_e32 v188, v188
	v_exp_f32_e32 v189, v189
	v_exp_f32_e32 v190, v190
	v_exp_f32_e32 v191, v191
	v_pk_mul_f32 v[48:49], v[52:53], v[48:49]
	v_pk_mul_f32 v[50:51], v[54:55], v[50:51]
	v_pk_mul_f32 v[56:57], v[60:61], v[56:57]
	v_pk_mul_f32 v[58:59], v[62:63], v[58:59]
	v_pk_fma_f32 v[184:185], v[184:185], v[182:183], v[182:183] op_sel_hi:[1,0,0]
	v_pk_fma_f32 v[186:187], v[186:187], v[182:183], v[182:183] op_sel_hi:[1,0,0]
	v_pk_fma_f32 v[188:189], v[188:189], v[182:183], v[182:183] op_sel_hi:[1,0,0]
	v_pk_fma_f32 v[190:191], v[190:191], v[182:183], v[182:183] op_sel_hi:[1,0,0]
	v_rcp_f32_e32 v184, v184
	v_rcp_f32_e32 v185, v185
	v_rcp_f32_e32 v186, v186
	v_rcp_f32_e32 v187, v187
	v_rcp_f32_e32 v188, v188
	v_rcp_f32_e32 v189, v189
	v_rcp_f32_e32 v190, v190
	v_rcp_f32_e32 v191, v191
	v_lshl_add_u64 v[178:179], s[38:39], 0, v[144:145]
	v_lshl_add_u64 v[178:179], v[178:179], 0, v[208:209]
	v_pk_mul_f32 v[48:49], v[48:49], v[184:185]
	v_pk_mul_f32 v[50:51], v[50:51], v[186:187]
	v_pk_mul_f32 v[56:57], v[56:57], v[188:189]
	v_pk_mul_f32 v[58:59], v[58:59], v[190:191]
	v_cvt_pk_bf16_f32 v48, v48, v49
	v_cvt_pk_bf16_f32 v49, v50, v51
	v_cvt_pk_bf16_f32 v50, v56, v57
	v_cvt_pk_bf16_f32 v51, v58, v59
	global_store_dwordx4 v[178:179], v[48:51], off sc1 nt
	v_mul_f32_e32 v180, 0xbfb8aa3b, v163
	v_mul_f32_e32 v182, v163, v163
	v_rcp_f32_e32 v182, v182
	v_pk_mul_f32 v[184:185], v[180:181], v[36:37] op_sel_hi:[0,1]
	v_pk_mul_f32 v[186:187], v[180:181], v[38:39] op_sel_hi:[0,1]
	v_pk_mul_f32 v[188:189], v[180:181], v[44:45] op_sel_hi:[0,1]
	v_pk_mul_f32 v[190:191], v[180:181], v[46:47] op_sel_hi:[0,1]
	v_exp_f32_e32 v184, v184
	v_exp_f32_e32 v185, v185
	v_exp_f32_e32 v186, v186
	v_exp_f32_e32 v187, v187
	v_exp_f32_e32 v188, v188
	v_exp_f32_e32 v189, v189
	v_exp_f32_e32 v190, v190
	v_exp_f32_e32 v191, v191
	v_pk_mul_f32 v[32:33], v[36:37], v[32:33]
	v_pk_mul_f32 v[34:35], v[38:39], v[34:35]
	v_pk_mul_f32 v[40:41], v[44:45], v[40:41]
	v_pk_mul_f32 v[42:43], v[46:47], v[42:43]
	v_pk_fma_f32 v[184:185], v[184:185], v[182:183], v[182:183] op_sel_hi:[1,0,0]
	v_pk_fma_f32 v[186:187], v[186:187], v[182:183], v[182:183] op_sel_hi:[1,0,0]
	v_pk_fma_f32 v[188:189], v[188:189], v[182:183], v[182:183] op_sel_hi:[1,0,0]
	v_pk_fma_f32 v[190:191], v[190:191], v[182:183], v[182:183] op_sel_hi:[1,0,0]
	v_rcp_f32_e32 v184, v184
	v_rcp_f32_e32 v185, v185
	v_rcp_f32_e32 v186, v186
	v_rcp_f32_e32 v187, v187
	v_rcp_f32_e32 v188, v188
	v_rcp_f32_e32 v189, v189
	v_rcp_f32_e32 v190, v190
	v_rcp_f32_e32 v191, v191
	v_lshl_add_u64 v[178:179], s[38:39], 0, v[146:147]
	v_lshl_add_u64 v[178:179], v[178:179], 0, v[208:209]
	v_pk_mul_f32 v[32:33], v[32:33], v[184:185]
	v_pk_mul_f32 v[34:35], v[34:35], v[186:187]
	v_pk_mul_f32 v[40:41], v[40:41], v[188:189]
	v_pk_mul_f32 v[42:43], v[42:43], v[190:191]
	v_cvt_pk_bf16_f32 v32, v32, v33
	v_cvt_pk_bf16_f32 v33, v34, v35
	v_cvt_pk_bf16_f32 v34, v40, v41
	v_cvt_pk_bf16_f32 v35, v42, v43
	global_store_dwordx4 v[178:179], v[32:35], off sc1 nt
	v_mul_f32_e32 v180, 0xbfb8aa3b, v162
	v_mul_f32_e32 v182, v162, v162
	v_rcp_f32_e32 v182, v182
	v_pk_mul_f32 v[184:185], v[180:181], v[20:21] op_sel_hi:[0,1]
	v_pk_mul_f32 v[186:187], v[180:181], v[22:23] op_sel_hi:[0,1]
	v_pk_mul_f32 v[188:189], v[180:181], v[28:29] op_sel_hi:[0,1]
	v_pk_mul_f32 v[190:191], v[180:181], v[30:31] op_sel_hi:[0,1]
	v_exp_f32_e32 v184, v184
	v_exp_f32_e32 v185, v185
	v_exp_f32_e32 v186, v186
	v_exp_f32_e32 v187, v187
	v_exp_f32_e32 v188, v188
	v_exp_f32_e32 v189, v189
	v_exp_f32_e32 v190, v190
	v_exp_f32_e32 v191, v191
	v_pk_mul_f32 v[16:17], v[20:21], v[16:17]
	v_pk_mul_f32 v[18:19], v[22:23], v[18:19]
	v_pk_mul_f32 v[24:25], v[28:29], v[24:25]
	v_pk_mul_f32 v[26:27], v[30:31], v[26:27]
	v_pk_fma_f32 v[184:185], v[184:185], v[182:183], v[182:183] op_sel_hi:[1,0,0]
	v_pk_fma_f32 v[186:187], v[186:187], v[182:183], v[182:183] op_sel_hi:[1,0,0]
	v_pk_fma_f32 v[188:189], v[188:189], v[182:183], v[182:183] op_sel_hi:[1,0,0]
	v_pk_fma_f32 v[190:191], v[190:191], v[182:183], v[182:183] op_sel_hi:[1,0,0]
	v_rcp_f32_e32 v184, v184
	v_rcp_f32_e32 v185, v185
	v_rcp_f32_e32 v186, v186
	v_rcp_f32_e32 v187, v187
	v_rcp_f32_e32 v188, v188
	v_rcp_f32_e32 v189, v189
	v_rcp_f32_e32 v190, v190
	v_rcp_f32_e32 v191, v191
	v_lshl_add_u64 v[178:179], s[38:39], 0, v[148:149]
	v_lshl_add_u64 v[178:179], v[178:179], 0, v[208:209]
	v_pk_mul_f32 v[16:17], v[16:17], v[184:185]
	v_pk_mul_f32 v[18:19], v[18:19], v[186:187]
	v_pk_mul_f32 v[24:25], v[24:25], v[188:189]
	v_pk_mul_f32 v[26:27], v[26:27], v[190:191]
	v_cvt_pk_bf16_f32 v16, v16, v17
	v_cvt_pk_bf16_f32 v17, v18, v19
	v_cvt_pk_bf16_f32 v18, v24, v25
	v_cvt_pk_bf16_f32 v19, v26, v27
	global_store_dwordx4 v[178:179], v[16:19], off sc1 nt
	v_mul_f32_e32 v180, 0xbfb8aa3b, v161
	v_mul_f32_e32 v182, v161, v161
	v_rcp_f32_e32 v182, v182
	v_pk_mul_f32 v[184:185], v[180:181], v[4:5] op_sel_hi:[0,1]
	v_pk_mul_f32 v[186:187], v[180:181], v[6:7] op_sel_hi:[0,1]
	v_pk_mul_f32 v[188:189], v[180:181], v[12:13] op_sel_hi:[0,1]
	v_pk_mul_f32 v[190:191], v[180:181], v[14:15] op_sel_hi:[0,1]
	v_exp_f32_e32 v184, v184
	v_exp_f32_e32 v185, v185
	v_exp_f32_e32 v186, v186
	v_exp_f32_e32 v187, v187
	v_exp_f32_e32 v188, v188
	v_exp_f32_e32 v189, v189
	v_exp_f32_e32 v190, v190
	v_exp_f32_e32 v191, v191
	v_pk_mul_f32 v[0:1], v[4:5], v[0:1]
	v_pk_mul_f32 v[2:3], v[6:7], v[2:3]
	v_pk_mul_f32 v[8:9], v[12:13], v[8:9]
	v_pk_mul_f32 v[10:11], v[14:15], v[10:11]
	v_pk_fma_f32 v[184:185], v[184:185], v[182:183], v[182:183] op_sel_hi:[1,0,0]
	v_pk_fma_f32 v[186:187], v[186:187], v[182:183], v[182:183] op_sel_hi:[1,0,0]
	v_pk_fma_f32 v[188:189], v[188:189], v[182:183], v[182:183] op_sel_hi:[1,0,0]
	v_pk_fma_f32 v[190:191], v[190:191], v[182:183], v[182:183] op_sel_hi:[1,0,0]
	v_rcp_f32_e32 v184, v184
	v_rcp_f32_e32 v185, v185
	v_rcp_f32_e32 v186, v186
	v_rcp_f32_e32 v187, v187
	v_rcp_f32_e32 v188, v188
	v_rcp_f32_e32 v189, v189
	v_rcp_f32_e32 v190, v190
	v_rcp_f32_e32 v191, v191
	v_lshl_add_u64 v[178:179], s[38:39], 0, v[150:151]
	v_lshl_add_u64 v[178:179], v[178:179], 0, v[208:209]
	v_pk_mul_f32 v[0:1], v[0:1], v[184:185]
	v_pk_mul_f32 v[2:3], v[2:3], v[186:187]
	v_pk_mul_f32 v[8:9], v[8:9], v[188:189]
	v_pk_mul_f32 v[10:11], v[10:11], v[190:191]
	v_cvt_pk_bf16_f32 v0, v0, v1
	v_cvt_pk_bf16_f32 v1, v2, v3
	v_cvt_pk_bf16_f32 v2, v8, v9
	v_cvt_pk_bf16_f32 v3, v10, v11
	s_andn2_b64 vcc, exec, s[36:37]
	s_mov_b64 s[2:3], -1
	global_store_dwordx4 v[178:179], v[0:3], off sc1 nt
	s_cbranch_vccnz .LBB0_567
	s_andn2_b64 vcc, exec, s[22:23]
	s_cbranch_vccnz .LBB0_566
	s_barrier
	s_branch .LBB0_566
